# v11 + residual (kind 1) epilogue drains its loads and stores at each row-group pair (vmcnt(0)) instead of keeping 10 ops in flight
# baseline (speedup 1.0000x reference)
;     static __device__ __forceinline__ void run(const f32x4 (&acc)[2][2][4][2], const Unit& u, int wr, int wc, int fr, int fq, const float* xin, float* xout, const float* gate, float gs, const float* lazy_ssq, const float* lazy_g, ...
;     ...
;         for (int bj = 0; bj < 2; ++bj) {
;             const unsigned col = col0 + bj * HALF;
;             f32x4 gv[2], lg[2], wv[2], w2[2];
; #pragma unroll
;             for (int n = 0; n < 2; ++n) {
;                 gv[n] = *(const f32x4*)(gate + (b * 9216u + col + 4 * n)) * gs;
;                 lg[n] = (f32x4){1.f, 1.f, 1.f, 1.f}; if (LAZY) lg[n] = *(const f32x4*)(lazy_g + col + 4 * n);
;                 wv[n] = (f32x4){0.f, 0.f, 0.f, 0.f}; w2[n] = (f32x4){1.f, 1.f, 1.f, 1.f};
;                 if (aout) { wv[n] = *(const f32x4*)(wg + col + 4 * n) * (*(const f32x4*)(wsc + (b * 9216u + col + 4 * n)) + 1.0f); if (WG2) { w2[n] = *(const f32x4*)(wg2 + col + 4 * n); wv[n] = wv[n] * w2[n]; } }
;             }
;             f32x4 xq[2][2][2];
;     ...
;             constexpr bool DEEP = !LAZY && !WG2;
;             if (DEEP) RES_LD(0, 0);
; #pragma unroll
;             for (int pp = 0; pp < 4; ++pp) {
;                 if (DEEP) { if (pp < 3) RES_LD((pp + 1) & 1, pp + 1); } else RES_LD(pp & 1, pp);
; #pragma unroll
;                 for (int j = 0; j < 2; ++j) { const int i_ = 2 * pp + j, ai = i_ >> 2, m = i_ & 3; const unsigned off = (row0 + ai * HALF + m * 16) * 1024u + col;
;                     const f32x4 xi0 = xq[pp & 1][j][0], xi1 = xq[pp & 1][j][1];
;                     f32x4 xo0 = gv[0] * acc[ai][bj][m][0], xo1 = gv[1] * acc[ai][bj][m][1];
;                     if (LAZY) { xo0 = xo0 + xi0 * lg[0] * rl[ai][m]; xo1 = xo1 + xi1 * lg[1] * rl[ai][m]; } else { xo0 = xo0 + xi0; xo1 = xo1 + xi1; }
;                     *(f32x4*)(xout + off) = xo0; *(f32x4*)(xout + off + 4) = xo1;
;                     if (aout) { const f32x4 a0 = xo0 * wv[0], a1 = xo1 * wv[1]; u32x4 w; w.x = cvt_pk_bf16(a0[0], a0[1]); w.y = cvt_pk_bf16(a0[2], a0[3]); w.z = cvt_pk_bf16(a1[0], a1[1]); w.w = cvt_pk_bf16(a1[2], a1[3]);
;                         *(u32x4*)(aout + off) = w;
;                         sq[ai][m] += ((xo0[0] * xo0[0] + xo0[1] * xo0[1]) + (xo0[2] * xo0[2] + xo0[3] * xo0[3])) + ((xo1[0] * xo1[0] + xo1[1] * xo1[1]) + (xo1[2] * xo1[2] + xo1[3] * xo1[3]));
.LBB0_487:
	s_lshl_b32 s42, s63, 8
	s_lshl_b32 s43, s65, 6
	s_add_i32 s43, s43, s42
	v_or_b32_e32 v172, s43, v230
	v_lshlrev_b32_e32 v207, 10, v172
	v_add_u32_e32 v176, v180, v207
	v_lshlrev_b64 v[204:205], 2, v[176:177]
	s_waitcnt vmcnt(0)
	v_pk_mul_f32 v[196:197], s[36:37], v[128:129] op_sel_hi:[0,1]
	v_lshl_add_u64 v[128:129], s[34:35], 0, v[204:205]
	v_add_u32_e32 v202, 0x4000, v176
	v_mov_b32_e32 v203, v177
	global_load_dwordx4 v[152:155], v[128:129], off offset:16
	global_load_dwordx4 v[156:159], v[128:129], off
	v_lshl_add_u64 v[128:129], v[202:203], 2, s[34:35]
	v_add_u32_e32 v200, 0x8000, v176
	v_mov_b32_e32 v201, v177
	v_add_u32_e32 v198, 0xc000, v176
	v_mov_b32_e32 v199, v177
	v_pk_mul_f32 v[190:191], s[36:37], v[132:133] op_sel_hi:[0,1]
	global_load_dwordx4 v[136:139], v[128:129], off offset:16
	global_load_dwordx4 v[144:147], v[128:129], off
	v_lshl_add_u64 v[128:129], v[200:201], 2, s[34:35]
	v_lshl_add_u64 v[132:133], v[198:199], 2, s[34:35]
	v_pk_mul_f32 v[192:193], s[36:37], v[134:135] op_sel_hi:[0,1]
	v_pk_mul_f32 v[194:195], s[36:37], v[130:131] op_sel_hi:[0,1]
	global_load_dwordx4 v[140:143], v[128:129], off offset:16
	global_load_dwordx4 v[148:151], v[128:129], off
	s_nop 0
	global_load_dwordx4 v[128:131], v[132:133], off offset:16
	s_nop 0
	global_load_dwordx4 v[132:135], v[132:133], off
	v_lshl_add_u64 v[204:205], s[28:29], 0, v[204:205]
	s_and_b64 vcc, exec, s[8:9]
	v_mov_b32_e32 v173, 0
	s_waitcnt vmcnt(0)
	v_pk_fma_f32 v[154:155], v[122:123], v[192:193], v[154:155]
	s_waitcnt vmcnt(0)
	v_pk_fma_f32 v[158:159], v[126:127], v[194:195], v[158:159]
	v_pk_fma_f32 v[156:157], v[124:125], v[196:197], v[156:157]
	v_pk_fma_f32 v[152:153], v[120:121], v[190:191], v[152:153]
	global_store_dwordx4 v[204:205], v[156:159], off
	global_store_dwordx4 v[204:205], v[152:155], off offset:16
	v_mov_b32_e32 v204, 0
	s_cbranch_vccnz .LBB0_489
	v_pk_mul_f32 v[210:211], v[184:185], v[158:159]
	v_pk_mul_f32 v[208:209], v[182:183], v[156:157]
	v_pk_mul_f32 v[212:213], v[188:189], v[154:155]
	v_pk_mul_f32 v[214:215], v[186:187], v[152:153]
	v_cvt_pk_bf16_f32 v208, v208, v209
	v_cvt_pk_bf16_f32 v209, v210, v211
	s_nop 0
	v_cvt_pk_bf16_f32 v210, v214, v215
	v_cvt_pk_bf16_f32 v211, v212, v213
	v_lshl_add_u64 v[212:213], v[176:177], 1, s[26:27]
	global_store_dwordx4 v[212:213], v[208:211], off
	s_nop 1
	v_mov_b32_e32 v209, v152
	v_mov_b32_e32 v152, v157
	v_mov_b32_e32 v157, v154
	v_mov_b32_e32 v154, v159
	v_mov_b32_e32 v208, v156
	v_pk_mul_f32 v[152:153], v[152:153], v[152:153]
	v_mov_b32_e32 v156, v158
	v_pk_mul_f32 v[154:155], v[154:155], v[154:155]
	v_pk_fma_f32 v[152:153], v[208:209], v[208:209], v[152:153]
	v_pk_fma_f32 v[154:155], v[156:157], v[156:157], v[154:155]
	s_nop 0
	v_pk_add_f32 v[152:153], v[152:153], v[154:155]
	s_nop 0
	v_add_f32_e32 v173, v152, v153
.LBB0_489:
	s_waitcnt vmcnt(0)
	v_pk_fma_f32 v[146:147], v[110:111], v[194:195], v[146:147]
	v_pk_fma_f32 v[144:145], v[108:109], v[196:197], v[144:145]
	v_pk_fma_f32 v[138:139], v[106:107], v[192:193], v[138:139]
	v_pk_fma_f32 v[136:137], v[104:105], v[190:191], v[136:137]
	v_lshl_add_u64 v[152:153], v[202:203], 2, s[28:29]
	s_and_b64 vcc, exec, s[8:9]
	global_store_dwordx4 v[152:153], v[144:147], off
	global_store_dwordx4 v[152:153], v[136:139], off offset:16
	s_cbranch_vccnz .LBB0_491
	v_pk_mul_f32 v[154:155], v[184:185], v[146:147]
	v_pk_mul_f32 v[152:153], v[182:183], v[144:145]
	v_pk_mul_f32 v[156:157], v[188:189], v[138:139]
	v_pk_mul_f32 v[158:159], v[186:187], v[136:137]
	v_cvt_pk_bf16_f32 v152, v152, v153
	v_cvt_pk_bf16_f32 v153, v154, v155
	s_nop 0
	v_cvt_pk_bf16_f32 v154, v158, v159
	v_cvt_pk_bf16_f32 v155, v156, v157
	v_lshl_add_u64 v[156:157], v[202:203], 1, s[26:27]
	global_store_dwordx4 v[156:157], v[152:155], off
	s_nop 1
	v_mov_b32_e32 v153, v136
	v_mov_b32_e32 v136, v145
	v_mov_b32_e32 v145, v138
	v_mov_b32_e32 v138, v147
	v_mov_b32_e32 v152, v144
	v_pk_mul_f32 v[136:137], v[136:137], v[136:137]
	v_mov_b32_e32 v144, v146
	v_pk_mul_f32 v[138:139], v[138:139], v[138:139]
	v_pk_fma_f32 v[136:137], v[152:153], v[152:153], v[136:137]
	v_pk_fma_f32 v[138:139], v[144:145], v[144:145], v[138:139]
	s_nop 0
	v_pk_add_f32 v[136:137], v[136:137], v[138:139]
	s_nop 0
	v_add_f32_e32 v204, v136, v137
.LBB0_491:
	v_add_u32_e32 v208, 0x20000, v207
	v_add_u32_e32 v202, v208, v180
	v_mov_b32_e32 v203, v177
	v_lshl_add_u64 v[136:137], v[202:203], 2, s[34:35]
	global_load_dwordx4 v[152:155], v[136:137], off offset:16
	global_load_dwordx4 v[156:159], v[136:137], off
	v_add_u32_e32 v136, 0x4000, v202
	v_mov_b32_e32 v137, v177
	v_lshl_add_u64 v[144:145], v[136:137], 2, s[34:35]
	global_load_dwordx4 v[136:139], v[144:145], off offset:16
	s_nop 0
	global_load_dwordx4 v[144:147], v[144:145], off
	s_waitcnt vmcnt(0)
	v_pk_fma_f32 v[150:151], v[94:95], v[194:195], v[150:151]
	v_pk_fma_f32 v[148:149], v[92:93], v[196:197], v[148:149]
	v_pk_fma_f32 v[142:143], v[90:91], v[192:193], v[142:143]
	v_pk_fma_f32 v[140:141], v[88:89], v[190:191], v[140:141]
	v_lshl_add_u64 v[210:211], v[200:201], 2, s[28:29]
	v_mov_b32_e32 v203, 0
	s_and_b64 vcc, exec, s[8:9]
	v_mov_b32_e32 v205, 0
	global_store_dwordx4 v[210:211], v[148:151], off
	global_store_dwordx4 v[210:211], v[140:143], off offset:16
	s_cbranch_vccnz .LBB0_493
	v_pk_mul_f32 v[212:213], v[184:185], v[150:151]
	v_pk_mul_f32 v[210:211], v[182:183], v[148:149]
	v_lshl_add_u64 v[200:201], v[200:201], 1, s[26:27]
	v_pk_mul_f32 v[214:215], v[188:189], v[142:143]
	v_pk_mul_f32 v[232:233], v[186:187], v[140:141]
	v_cvt_pk_bf16_f32 v210, v210, v211
	v_cvt_pk_bf16_f32 v211, v212, v213
	s_nop 0
	v_cvt_pk_bf16_f32 v212, v232, v233
	v_cvt_pk_bf16_f32 v213, v214, v215
	global_store_dwordx4 v[200:201], v[210:213], off
	v_mov_b32_e32 v201, v140
	v_mov_b32_e32 v140, v149
	v_mov_b32_e32 v149, v142
	v_mov_b32_e32 v142, v151
	v_mov_b32_e32 v200, v148
	v_pk_mul_f32 v[140:141], v[140:141], v[140:141]
	v_mov_b32_e32 v148, v150
	v_pk_mul_f32 v[142:143], v[142:143], v[142:143]
	v_pk_fma_f32 v[140:141], v[200:201], v[200:201], v[140:141]
	v_pk_fma_f32 v[142:143], v[148:149], v[148:149], v[142:143]
	s_nop 0
	v_pk_add_f32 v[140:141], v[140:141], v[142:143]
	s_nop 0
	v_add_f32_e32 v205, v140, v141
; __device__ __forceinline__ unsigned cvt_pk_bf16(float lo, float hi) { unsigned r; asm volatile("v_cvt_pk_bf16_f32 %0, %1, %2" : "=v"(r) : "v"(lo), "v"(hi)); return r; }
; #define RES_LD(buf, pp) do { _Pragma("unroll") for (int j = 0; j < 2; ++j) { const int i_ = 2 * (pp) + j; const unsigned off_ = (row0 + (i_ >> 2) * HALF + (i_ & 3) * 16) * 1024u + col; \
;                 xq[buf][j][0] = *(const f32x4*)(xin + off_); xq[buf][j][1] = *(const f32x4*)(xin + off_ + 4); } } while (0)
;     static __device__ __forceinline__ void run(const f32x4 (&acc)[2][2][4][2], const Unit& u, int wr, int wc, int fr, int fq, const float* xin, float* xout, const float* gate, float gs, const float* lazy_ssq, const float* lazy_g, ...
;     ...
;             constexpr bool DEEP = !LAZY && !WG2;
;             if (DEEP) RES_LD(0, 0);
; #pragma unroll
;             for (int pp = 0; pp < 4; ++pp) {
;                 if (DEEP) { if (pp < 3) RES_LD((pp + 1) & 1, pp + 1); } else RES_LD(pp & 1, pp);
; #pragma unroll
;                 for (int j = 0; j < 2; ++j) { const int i_ = 2 * pp + j, ai = i_ >> 2, m = i_ & 3; const unsigned off = (row0 + ai * HALF + m * 16) * 1024u + col;
;                     const f32x4 xi0 = xq[pp & 1][j][0], xi1 = xq[pp & 1][j][1];
;                     f32x4 xo0 = gv[0] * acc[ai][bj][m][0], xo1 = gv[1] * acc[ai][bj][m][1];
;                     if (LAZY) { xo0 = xo0 + xi0 * lg[0] * rl[ai][m]; xo1 = xo1 + xi1 * lg[1] * rl[ai][m]; } else { xo0 = xo0 + xi0; xo1 = xo1 + xi1; }
;                     *(f32x4*)(xout + off) = xo0; *(f32x4*)(xout + off + 4) = xo1;
;                     if (aout) { const f32x4 a0 = xo0 * wv[0], a1 = xo1 * wv[1]; u32x4 w; w.x = cvt_pk_bf16(a0[0], a0[1]); w.y = cvt_pk_bf16(a0[2], a0[3]); w.z = cvt_pk_bf16(a1[0], a1[1]); w.w = cvt_pk_bf16(a1[2], a1[3]);
;                         *(u32x4*)(aout + off) = w;
;                         sq[ai][m] += ((xo0[0] * xo0[0] + xo0[1] * xo0[1]) + (xo0[2] * xo0[2] + xo0[3] * xo0[3])) + ((xo1[0] * xo1[0] + xo1[1] * xo1[1]) + (xo1[2] * xo1[2] + xo1[3] * xo1[3]));
;                         if (WG2) { const f32x4 b0 = xo0 * w2[0], b1 = xo1 * w2[1]; sqb[ai][m] += ((b0[0] * b0[0] + b0[1] * b0[1]) + (b0[2] * b0[2] + b0[3] * b0[3])) + ((b1[0] * b1[0] + b1[1] * b1[1]) + (b1[2] * b1[2] + b1[3] * b1[3])); } } }
.LBB0_493:
	s_waitcnt vmcnt(0)
	v_pk_fma_f32 v[134:135], v[78:79], v[194:195], v[134:135]
	v_pk_fma_f32 v[132:133], v[76:77], v[196:197], v[132:133]
	v_pk_fma_f32 v[130:131], v[74:75], v[192:193], v[130:131]
	v_pk_fma_f32 v[128:129], v[72:73], v[190:191], v[128:129]
	v_lshl_add_u64 v[140:141], v[198:199], 2, s[28:29]
	s_and_b64 vcc, exec, s[8:9]
	global_store_dwordx4 v[140:141], v[132:135], off
	global_store_dwordx4 v[140:141], v[128:131], off offset:16
	s_cbranch_vccnz .LBB0_495
	v_pk_mul_f32 v[142:143], v[184:185], v[134:135]
	v_pk_mul_f32 v[140:141], v[182:183], v[132:133]
	v_pk_mul_f32 v[148:149], v[188:189], v[130:131]
	v_pk_mul_f32 v[150:151], v[186:187], v[128:129]
	v_cvt_pk_bf16_f32 v140, v140, v141
	v_cvt_pk_bf16_f32 v141, v142, v143
	s_nop 0
	v_cvt_pk_bf16_f32 v142, v150, v151
	v_cvt_pk_bf16_f32 v143, v148, v149
	v_lshl_add_u64 v[148:149], v[198:199], 1, s[26:27]
	global_store_dwordx4 v[148:149], v[140:143], off
	s_nop 1
	v_mov_b32_e32 v141, v128
	v_mov_b32_e32 v128, v133
	v_mov_b32_e32 v133, v130
	v_mov_b32_e32 v130, v135
	v_mov_b32_e32 v140, v132
	v_pk_mul_f32 v[128:129], v[128:129], v[128:129]
	v_mov_b32_e32 v132, v134
	v_pk_mul_f32 v[130:131], v[130:131], v[130:131]
	v_pk_fma_f32 v[128:129], v[140:141], v[140:141], v[128:129]
	v_pk_fma_f32 v[130:131], v[132:133], v[132:133], v[130:131]
	s_nop 0
	v_pk_add_f32 v[128:129], v[128:129], v[130:131]
	s_nop 0
	v_add_f32_e32 v203, v128, v129
.LBB0_495:
	s_nop 0
	v_add_u32_e32 v128, 0x8000, v202
	v_mov_b32_e32 v129, v177
	v_lshl_add_u64 v[128:129], v[128:129], 2, s[34:35]
	global_load_dwordx4 v[140:143], v[128:129], off offset:16
	global_load_dwordx4 v[148:151], v[128:129], off
	v_add_u32_e32 v128, 0xc000, v202
	v_mov_b32_e32 v129, v177
	v_lshl_add_u64 v[132:133], v[128:129], 2, s[34:35]
	global_load_dwordx4 v[128:131], v[132:133], off offset:16
	s_nop 0
	global_load_dwordx4 v[132:135], v[132:133], off
	v_add_u32_e32 v198, 0x20000, v176
	v_mov_b32_e32 v199, v177
	s_waitcnt vmcnt(0)
	v_pk_fma_f32 v[158:159], v[62:63], v[194:195], v[158:159]
	v_pk_fma_f32 v[156:157], v[60:61], v[196:197], v[156:157]
	v_lshl_add_u64 v[200:201], v[198:199], 2, s[28:29]
	v_pk_fma_f32 v[154:155], v[58:59], v[192:193], v[154:155]
	v_pk_fma_f32 v[152:153], v[56:57], v[190:191], v[152:153]
	global_store_dwordx4 v[200:201], v[156:159], off
	global_store_dwordx4 v[200:201], v[152:155], off offset:16
	v_mov_b32_e32 v200, 0
	s_and_b64 vcc, exec, s[8:9]
	v_mov_b32_e32 v201, 0
	s_cbranch_vccnz .LBB0_497
	v_pk_mul_f32 v[212:213], v[184:185], v[158:159]
	v_pk_mul_f32 v[210:211], v[182:183], v[156:157]
	v_lshl_add_u64 v[198:199], v[198:199], 1, s[26:27]
	v_pk_mul_f32 v[214:215], v[188:189], v[154:155]
	v_pk_mul_f32 v[232:233], v[186:187], v[152:153]
	v_cvt_pk_bf16_f32 v210, v210, v211
	v_cvt_pk_bf16_f32 v211, v212, v213
	s_nop 0
	v_cvt_pk_bf16_f32 v212, v232, v233
	v_cvt_pk_bf16_f32 v213, v214, v215
	global_store_dwordx4 v[198:199], v[210:213], off
	v_mov_b32_e32 v199, v152
	v_mov_b32_e32 v152, v157
	v_mov_b32_e32 v157, v154
	v_mov_b32_e32 v154, v159
	v_mov_b32_e32 v198, v156
	v_pk_mul_f32 v[152:153], v[152:153], v[152:153]
	v_mov_b32_e32 v156, v158
	v_pk_mul_f32 v[154:155], v[154:155], v[154:155]
	v_pk_fma_f32 v[152:153], v[198:199], v[198:199], v[152:153]
	v_pk_fma_f32 v[154:155], v[156:157], v[156:157], v[154:155]
	s_nop 0
	v_pk_add_f32 v[152:153], v[152:153], v[154:155]
	s_nop 0
	v_add_f32_e32 v201, v152, v153
; __device__ __forceinline__ unsigned cvt_pk_bf16(float lo, float hi) { unsigned r; asm volatile("v_cvt_pk_bf16_f32 %0, %1, %2" : "=v"(r) : "v"(lo), "v"(hi)); return r; }
; #define RES_LD(buf, pp) do { _Pragma("unroll") for (int j = 0; j < 2; ++j) { const int i_ = 2 * (pp) + j; const unsigned off_ = (row0 + (i_ >> 2) * HALF + (i_ & 3) * 16) * 1024u + col; \
;                 xq[buf][j][0] = *(const f32x4*)(xin + off_); xq[buf][j][1] = *(const f32x4*)(xin + off_ + 4); } } while (0)
;     static __device__ __forceinline__ void run(const f32x4 (&acc)[2][2][4][2], const Unit& u, int wr, int wc, int fr, int fq, const float* xin, float* xout, const float* gate, float gs, const float* lazy_ssq, const float* lazy_g, ...
;     ...
;             constexpr bool DEEP = !LAZY && !WG2;
;             if (DEEP) RES_LD(0, 0);
; #pragma unroll
;             for (int pp = 0; pp < 4; ++pp) {
;                 if (DEEP) { if (pp < 3) RES_LD((pp + 1) & 1, pp + 1); } else RES_LD(pp & 1, pp);
; #pragma unroll
;                 for (int j = 0; j < 2; ++j) { const int i_ = 2 * pp + j, ai = i_ >> 2, m = i_ & 3; const unsigned off = (row0 + ai * HALF + m * 16) * 1024u + col;
;                     const f32x4 xi0 = xq[pp & 1][j][0], xi1 = xq[pp & 1][j][1];
;                     f32x4 xo0 = gv[0] * acc[ai][bj][m][0], xo1 = gv[1] * acc[ai][bj][m][1];
;                     if (LAZY) { xo0 = xo0 + xi0 * lg[0] * rl[ai][m]; xo1 = xo1 + xi1 * lg[1] * rl[ai][m]; } else { xo0 = xo0 + xi0; xo1 = xo1 + xi1; }
;                     *(f32x4*)(xout + off) = xo0; *(f32x4*)(xout + off + 4) = xo1;
;                     if (aout) { const f32x4 a0 = xo0 * wv[0], a1 = xo1 * wv[1]; u32x4 w; w.x = cvt_pk_bf16(a0[0], a0[1]); w.y = cvt_pk_bf16(a0[2], a0[3]); w.z = cvt_pk_bf16(a1[0], a1[1]); w.w = cvt_pk_bf16(a1[2], a1[3]);
;                         *(u32x4*)(aout + off) = w;
;                         sq[ai][m] += ((xo0[0] * xo0[0] + xo0[1] * xo0[1]) + (xo0[2] * xo0[2] + xo0[3] * xo0[3])) + ((xo1[0] * xo1[0] + xo1[1] * xo1[1]) + (xo1[2] * xo1[2] + xo1[3] * xo1[3]));
;                         if (WG2) { const f32x4 b0 = xo0 * w2[0], b1 = xo1 * w2[1]; sqb[ai][m] += ((b0[0] * b0[0] + b0[1] * b0[1]) + (b0[2] * b0[2] + b0[3] * b0[3])) + ((b1[0] * b1[0] + b1[1] * b1[1]) + (b1[2] * b1[2] + b1[3] * b1[3])); } } }
.LBB0_497:
	v_add_u32_e32 v152, 0x24000, v176
	v_mov_b32_e32 v153, v177
	s_waitcnt vmcnt(0)
	v_pk_fma_f32 v[146:147], v[46:47], v[194:195], v[146:147]
	v_pk_fma_f32 v[144:145], v[44:45], v[196:197], v[144:145]
	v_pk_fma_f32 v[138:139], v[42:43], v[192:193], v[138:139]
	v_pk_fma_f32 v[136:137], v[40:41], v[190:191], v[136:137]
	v_lshl_add_u64 v[154:155], v[152:153], 2, s[28:29]
	s_and_b64 vcc, exec, s[8:9]
	global_store_dwordx4 v[154:155], v[144:147], off
	global_store_dwordx4 v[154:155], v[136:139], off offset:16
	s_cbranch_vccnz .LBB0_499
	v_pk_mul_f32 v[156:157], v[184:185], v[146:147]
	v_pk_mul_f32 v[154:155], v[182:183], v[144:145]
	v_lshl_add_u64 v[152:153], v[152:153], 1, s[26:27]
	v_pk_mul_f32 v[158:159], v[188:189], v[138:139]
	v_pk_mul_f32 v[198:199], v[186:187], v[136:137]
	v_cvt_pk_bf16_f32 v154, v154, v155
	v_cvt_pk_bf16_f32 v155, v156, v157
	s_nop 0
	v_cvt_pk_bf16_f32 v156, v198, v199
	v_cvt_pk_bf16_f32 v157, v158, v159
	global_store_dwordx4 v[152:153], v[154:157], off
	v_mov_b32_e32 v153, v136
	v_mov_b32_e32 v136, v145
	v_mov_b32_e32 v145, v138
	v_mov_b32_e32 v138, v147
	v_mov_b32_e32 v152, v144
	v_pk_mul_f32 v[136:137], v[136:137], v[136:137]
	v_mov_b32_e32 v144, v146
	v_pk_mul_f32 v[138:139], v[138:139], v[138:139]
	v_pk_fma_f32 v[136:137], v[152:153], v[152:153], v[136:137]
	v_pk_fma_f32 v[138:139], v[144:145], v[144:145], v[138:139]
	s_nop 0
	v_pk_add_f32 v[136:137], v[136:137], v[138:139]
	s_nop 0
	v_add_f32_e32 v200, v136, v137
.LBB0_499:
	v_add_u32_e32 v144, 0x28000, v176
	v_mov_b32_e32 v145, v177
	s_waitcnt vmcnt(0)
	v_pk_fma_f32 v[138:139], v[30:31], v[194:195], v[150:151]
	v_pk_fma_f32 v[136:137], v[28:29], v[196:197], v[148:149]
	v_pk_fma_f32 v[142:143], v[26:27], v[192:193], v[142:143]
	v_pk_fma_f32 v[140:141], v[24:25], v[190:191], v[140:141]
	v_lshl_add_u64 v[146:147], v[144:145], 2, s[28:29]
	v_mov_b32_e32 v202, 0
	s_and_b64 vcc, exec, s[8:9]
	v_mov_b32_e32 v206, 0
	global_store_dwordx4 v[146:147], v[136:139], off
	global_store_dwordx4 v[146:147], v[140:143], off offset:16
	s_cbranch_vccnz .LBB0_501
	v_pk_mul_f32 v[148:149], v[184:185], v[138:139]
	v_pk_mul_f32 v[146:147], v[182:183], v[136:137]
	v_lshl_add_u64 v[144:145], v[144:145], 1, s[26:27]
	v_pk_mul_f32 v[150:151], v[188:189], v[142:143]
	v_pk_mul_f32 v[152:153], v[186:187], v[140:141]
	v_cvt_pk_bf16_f32 v146, v146, v147
	v_cvt_pk_bf16_f32 v147, v148, v149
	s_nop 0
	v_cvt_pk_bf16_f32 v148, v152, v153
	v_cvt_pk_bf16_f32 v149, v150, v151
	global_store_dwordx4 v[144:145], v[146:149], off
	v_mov_b32_e32 v145, v140
	v_mov_b32_e32 v140, v137
	v_mov_b32_e32 v144, v136
	v_pk_mul_f32 v[136:137], v[140:141], v[140:141]
	v_mov_b32_e32 v141, v142
	v_mov_b32_e32 v142, v139
	v_mov_b32_e32 v140, v138
	v_pk_mul_f32 v[138:139], v[142:143], v[142:143]
	v_pk_fma_f32 v[136:137], v[144:145], v[144:145], v[136:137]
	v_pk_fma_f32 v[138:139], v[140:141], v[140:141], v[138:139]
	s_nop 0
	v_pk_add_f32 v[136:137], v[136:137], v[138:139]
	s_nop 0
	v_add_f32_e32 v206, v136, v137
.LBB0_501:
	v_add_u32_e32 v176, 0x2c000, v176
	s_waitcnt vmcnt(0)
	v_pk_fma_f32 v[134:135], v[14:15], v[194:195], v[134:135]
	v_pk_fma_f32 v[132:133], v[12:13], v[196:197], v[132:133]
	v_pk_fma_f32 v[130:131], v[10:11], v[192:193], v[130:131]
	v_pk_fma_f32 v[128:129], v[8:9], v[190:191], v[128:129]
	v_lshl_add_u64 v[136:137], v[176:177], 2, s[28:29]
	s_and_b64 vcc, exec, s[8:9]
	global_store_dwordx4 v[136:137], v[132:135], off
	global_store_dwordx4 v[136:137], v[128:131], off offset:16
	s_cbranch_vccnz .LBB0_503
	v_pk_mul_f32 v[138:139], v[184:185], v[134:135]
	v_pk_mul_f32 v[136:137], v[182:183], v[132:133]
	v_pk_mul_f32 v[140:141], v[188:189], v[130:131]
	v_pk_mul_f32 v[142:143], v[186:187], v[128:129]
	v_cvt_pk_bf16_f32 v136, v136, v137
	v_cvt_pk_bf16_f32 v137, v138, v139
	s_nop 0
	v_cvt_pk_bf16_f32 v138, v142, v143
	v_cvt_pk_bf16_f32 v139, v140, v141
	v_lshl_add_u64 v[140:141], v[176:177], 1, s[26:27]
	global_store_dwordx4 v[140:141], v[136:139], off
	s_nop 1
	v_mov_b32_e32 v137, v128
	v_mov_b32_e32 v128, v133
	v_mov_b32_e32 v133, v130
	v_mov_b32_e32 v130, v135
	v_mov_b32_e32 v136, v132
	v_pk_mul_f32 v[128:129], v[128:129], v[128:129]
	v_mov_b32_e32 v132, v134
	v_pk_mul_f32 v[130:131], v[130:131], v[130:131]
	v_pk_fma_f32 v[128:129], v[136:137], v[136:137], v[128:129]
	v_pk_fma_f32 v[130:131], v[132:133], v[132:133], v[130:131]
	s_nop 0
	v_pk_add_f32 v[128:129], v[128:129], v[130:131]
	s_nop 0
	v_add_f32_e32 v202, v128, v129

; __device__ __forceinline__ unsigned cvt_pk_bf16(float lo, float hi) { unsigned r; asm volatile("v_cvt_pk_bf16_f32 %0, %1, %2" : "=v"(r) : "v"(lo), "v"(hi)); return r; }
; #define RES_LD(buf, pp) do { _Pragma("unroll") for (int j = 0; j < 2; ++j) { const int i_ = 2 * (pp) + j; const unsigned off_ = (row0 + (i_ >> 2) * HALF + (i_ & 3) * 16) * 1024u + col; \
;                 xq[buf][j][0] = *(const f32x4*)(xin + off_); xq[buf][j][1] = *(const f32x4*)(xin + off_ + 4); } } while (0)
;     static __device__ __forceinline__ void run(const f32x4 (&acc)[2][2][4][2], const Unit& u, int wr, int wc, int fr, int fq, const float* xin, float* xout, const float* gate, float gs, const float* lazy_ssq, const float* lazy_g, ...
;     ...
;             constexpr bool DEEP = !LAZY && !WG2;
;             if (DEEP) RES_LD(0, 0);
; #pragma unroll
;             for (int pp = 0; pp < 4; ++pp) {
;                 if (DEEP) { if (pp < 3) RES_LD((pp + 1) & 1, pp + 1); } else RES_LD(pp & 1, pp);
; #pragma unroll
;                 for (int j = 0; j < 2; ++j) { const int i_ = 2 * pp + j, ai = i_ >> 2, m = i_ & 3; const unsigned off = (row0 + ai * HALF + m * 16) * 1024u + col;
;                     const f32x4 xi0 = xq[pp & 1][j][0], xi1 = xq[pp & 1][j][1];
;                     f32x4 xo0 = gv[0] * acc[ai][bj][m][0], xo1 = gv[1] * acc[ai][bj][m][1];
;                     if (LAZY) { xo0 = xo0 + xi0 * lg[0] * rl[ai][m]; xo1 = xo1 + xi1 * lg[1] * rl[ai][m]; } else { xo0 = xo0 + xi0; xo1 = xo1 + xi1; }
;                     *(f32x4*)(xout + off) = xo0; *(f32x4*)(xout + off + 4) = xo1;
;                     if (aout) { const f32x4 a0 = xo0 * wv[0], a1 = xo1 * wv[1]; u32x4 w; w.x = cvt_pk_bf16(a0[0], a0[1]); w.y = cvt_pk_bf16(a0[2], a0[3]); w.z = cvt_pk_bf16(a1[0], a1[1]); w.w = cvt_pk_bf16(a1[2], a1[3]);
;                         *(u32x4*)(aout + off) = w;
;                         sq[ai][m] += ((xo0[0] * xo0[0] + xo0[1] * xo0[1]) + (xo0[2] * xo0[2] + xo0[3] * xo0[3])) + ((xo1[0] * xo1[0] + xo1[1] * xo1[1]) + (xo1[2] * xo1[2] + xo1[3] * xo1[3]));
;                         if (WG2) { const f32x4 b0 = xo0 * w2[0], b1 = xo1 * w2[1]; sqb[ai][m] += ((b0[0] * b0[0] + b0[1] * b0[1]) + (b0[2] * b0[2] + b0[3] * b0[3])) + ((b1[0] * b1[0] + b1[1] * b1[1]) + (b1[2] * b1[2] + b1[3] * b1[3])); } } }
.LBB0_507:
	v_add_u32_e32 v176, v209, v207
	v_lshlrev_b64 v[214:215], 2, v[176:177]
	v_lshl_add_u64 v[128:129], s[34:35], 0, v[214:215]
	v_add_u32_e32 v198, 0x4000, v176
	v_mov_b32_e32 v199, v177
	global_load_dwordx4 v[210:213], v[128:129], off offset:16
	global_load_dwordx4 v[232:235], v[128:129], off
	v_lshl_add_u64 v[128:129], v[198:199], 2, s[34:35]
	v_add_u32_e32 v196, 0x8000, v176
	v_mov_b32_e32 v197, v177
	v_add_u32_e32 v194, 0xc000, v176
	v_mov_b32_e32 v195, v177
	global_load_dwordx4 v[132:135], v[128:129], off offset:16
	global_load_dwordx4 v[152:155], v[128:129], off
	v_lshl_add_u64 v[128:129], v[196:197], 2, s[34:35]
	v_lshl_add_u64 v[136:137], v[194:195], 2, s[34:35]
	global_load_dwordx4 v[144:147], v[128:129], off offset:16
	global_load_dwordx4 v[148:151], v[128:129], off
	s_nop 0
	global_load_dwordx4 v[128:131], v[136:137], off offset:16
	s_nop 0
	global_load_dwordx4 v[136:139], v[136:137], off
	s_mov_b32 s37, s36
	s_mov_b32 s38, s36
	s_mov_b32 s39, s36
	s_waitcnt vmcnt(8)
	v_pk_mul_f32 v[188:189], s[38:39], v[158:159]
	v_pk_mul_f32 v[174:175], s[36:37], v[156:157]
	v_pk_mul_f32 v[190:191], s[38:39], v[142:143]
	v_pk_mul_f32 v[192:193], s[36:37], v[140:141]
	s_and_b64 vcc, exec, s[8:9]
	v_lshl_add_u64 v[214:215], s[28:29], 0, v[214:215]
	s_waitcnt vmcnt(0)
	v_pk_fma_f32 v[142:143], v[114:115], v[188:189], v[212:213]
	s_waitcnt vmcnt(0)
	v_pk_fma_f32 v[158:159], v[118:119], v[190:191], v[234:235]
	v_pk_fma_f32 v[156:157], v[116:117], v[192:193], v[232:233]
	v_pk_fma_f32 v[140:141], v[112:113], v[174:175], v[210:211]
	global_store_dwordx4 v[214:215], v[156:159], off
	global_store_dwordx4 v[214:215], v[140:143], off offset:16
	s_cbranch_vccnz .LBB0_509
	v_pk_mul_f32 v[212:213], v[184:185], v[158:159]
	v_pk_mul_f32 v[210:211], v[182:183], v[156:157]
	v_pk_mul_f32 v[214:215], v[186:187], v[142:143]
	v_pk_mul_f32 v[232:233], v[180:181], v[140:141]
	v_cvt_pk_bf16_f32 v210, v210, v211
	v_cvt_pk_bf16_f32 v211, v212, v213
	s_nop 0
	v_cvt_pk_bf16_f32 v212, v232, v233
	v_cvt_pk_bf16_f32 v213, v214, v215
	v_lshl_add_u64 v[214:215], v[176:177], 1, s[26:27]
	global_store_dwordx4 v[214:215], v[210:213], off
	s_nop 1
	v_mov_b32_e32 v211, v140
	v_mov_b32_e32 v140, v157
	v_mov_b32_e32 v157, v142
	v_mov_b32_e32 v142, v159
	v_mov_b32_e32 v210, v156
	v_pk_mul_f32 v[140:141], v[140:141], v[140:141]
	v_mov_b32_e32 v156, v158
	v_pk_mul_f32 v[142:143], v[142:143], v[142:143]
	v_pk_fma_f32 v[140:141], v[210:211], v[210:211], v[140:141]
	v_pk_fma_f32 v[142:143], v[156:157], v[156:157], v[142:143]
	s_nop 0
	v_pk_add_f32 v[140:141], v[140:141], v[142:143]
	s_nop 0
	v_add_f32_e32 v140, v140, v141
	v_add_f32_e32 v173, v173, v140
.LBB0_509:
	s_waitcnt vmcnt(0)
	v_pk_fma_f32 v[142:143], v[102:103], v[190:191], v[154:155]
	v_pk_fma_f32 v[140:141], v[100:101], v[192:193], v[152:153]
	v_pk_fma_f32 v[134:135], v[98:99], v[188:189], v[134:135]
	v_pk_fma_f32 v[132:133], v[96:97], v[174:175], v[132:133]
	v_lshl_add_u64 v[152:153], v[198:199], 2, s[28:29]
	s_and_b64 vcc, exec, s[8:9]
	global_store_dwordx4 v[152:153], v[140:143], off
	global_store_dwordx4 v[152:153], v[132:135], off offset:16
	s_cbranch_vccnz .LBB0_511
	v_pk_mul_f32 v[154:155], v[184:185], v[142:143]
	v_pk_mul_f32 v[152:153], v[182:183], v[140:141]
	v_pk_mul_f32 v[156:157], v[186:187], v[134:135]
	v_pk_mul_f32 v[158:159], v[180:181], v[132:133]
	v_cvt_pk_bf16_f32 v152, v152, v153
	v_cvt_pk_bf16_f32 v153, v154, v155
	s_nop 0
	v_cvt_pk_bf16_f32 v154, v158, v159
	v_cvt_pk_bf16_f32 v155, v156, v157
	v_lshl_add_u64 v[156:157], v[198:199], 1, s[26:27]
	global_store_dwordx4 v[156:157], v[152:155], off
	s_nop 1
	v_mov_b32_e32 v153, v132
	v_mov_b32_e32 v132, v141
	v_mov_b32_e32 v141, v134
	v_mov_b32_e32 v134, v143
	v_mov_b32_e32 v152, v140
	v_pk_mul_f32 v[132:133], v[132:133], v[132:133]
	v_mov_b32_e32 v140, v142
	v_pk_mul_f32 v[134:135], v[134:135], v[134:135]
	v_pk_fma_f32 v[132:133], v[152:153], v[152:153], v[132:133]
	v_pk_fma_f32 v[134:135], v[140:141], v[140:141], v[134:135]
	s_nop 0
	v_pk_add_f32 v[132:133], v[132:133], v[134:135]
	s_nop 0
	v_add_f32_e32 v132, v132, v133
	v_add_f32_e32 v204, v204, v132
.LBB0_511:
	v_add_u32_e32 v198, v208, v209
	v_mov_b32_e32 v199, v177
	v_lshl_add_u64 v[132:133], v[198:199], 2, s[34:35]
	global_load_dwordx4 v[152:155], v[132:133], off offset:16
	global_load_dwordx4 v[156:159], v[132:133], off
	v_add_u32_e32 v132, 0x4000, v198
	v_mov_b32_e32 v133, v177
	v_lshl_add_u64 v[140:141], v[132:133], 2, s[34:35]
	global_load_dwordx4 v[132:135], v[140:141], off offset:16
	s_nop 0
	global_load_dwordx4 v[140:143], v[140:141], off
	s_waitcnt vmcnt(0)
	v_pk_fma_f32 v[150:151], v[86:87], v[190:191], v[150:151]
	v_pk_fma_f32 v[148:149], v[84:85], v[192:193], v[148:149]
	v_pk_fma_f32 v[146:147], v[82:83], v[188:189], v[146:147]
	v_pk_fma_f32 v[144:145], v[80:81], v[174:175], v[144:145]
	v_lshl_add_u64 v[208:209], v[196:197], 2, s[28:29]
	s_and_b64 vcc, exec, s[8:9]
	global_store_dwordx4 v[208:209], v[148:151], off
	global_store_dwordx4 v[208:209], v[144:147], off offset:16
	s_cbranch_vccnz .LBB0_513
	v_pk_mul_f32 v[210:211], v[184:185], v[150:151]
	v_pk_mul_f32 v[208:209], v[182:183], v[148:149]
	v_lshl_add_u64 v[196:197], v[196:197], 1, s[26:27]
	v_pk_mul_f32 v[212:213], v[186:187], v[146:147]
	v_pk_mul_f32 v[214:215], v[180:181], v[144:145]
	v_cvt_pk_bf16_f32 v208, v208, v209
	v_cvt_pk_bf16_f32 v209, v210, v211
	s_nop 0
	v_cvt_pk_bf16_f32 v210, v214, v215
	v_cvt_pk_bf16_f32 v211, v212, v213
	global_store_dwordx4 v[196:197], v[208:211], off
	v_mov_b32_e32 v197, v144
	v_mov_b32_e32 v144, v149
	v_mov_b32_e32 v149, v146
	v_mov_b32_e32 v146, v151
	v_mov_b32_e32 v196, v148
	v_pk_mul_f32 v[144:145], v[144:145], v[144:145]
	v_mov_b32_e32 v148, v150
	v_pk_mul_f32 v[146:147], v[146:147], v[146:147]
	v_pk_fma_f32 v[144:145], v[196:197], v[196:197], v[144:145]
	v_pk_fma_f32 v[146:147], v[148:149], v[148:149], v[146:147]
	s_nop 0
	v_pk_add_f32 v[144:145], v[144:145], v[146:147]
	s_nop 0
	v_add_f32_e32 v144, v144, v145
	v_add_f32_e32 v205, v205, v144
; __device__ __forceinline__ unsigned cvt_pk_bf16(float lo, float hi) { unsigned r; asm volatile("v_cvt_pk_bf16_f32 %0, %1, %2" : "=v"(r) : "v"(lo), "v"(hi)); return r; }
; #define RES_LD(buf, pp) do { _Pragma("unroll") for (int j = 0; j < 2; ++j) { const int i_ = 2 * (pp) + j; const unsigned off_ = (row0 + (i_ >> 2) * HALF + (i_ & 3) * 16) * 1024u + col; \
;                 xq[buf][j][0] = *(const f32x4*)(xin + off_); xq[buf][j][1] = *(const f32x4*)(xin + off_ + 4); } } while (0)
;     static __device__ __forceinline__ void run(const f32x4 (&acc)[2][2][4][2], const Unit& u, int wr, int wc, int fr, int fq, const float* xin, float* xout, const float* gate, float gs, const float* lazy_ssq, const float* lazy_g, ...
;     ...
;             constexpr bool DEEP = !LAZY && !WG2;
;             if (DEEP) RES_LD(0, 0);
; #pragma unroll
;             for (int pp = 0; pp < 4; ++pp) {
;                 if (DEEP) { if (pp < 3) RES_LD((pp + 1) & 1, pp + 1); } else RES_LD(pp & 1, pp);
; #pragma unroll
;                 for (int j = 0; j < 2; ++j) { const int i_ = 2 * pp + j, ai = i_ >> 2, m = i_ & 3; const unsigned off = (row0 + ai * HALF + m * 16) * 1024u + col;
;                     const f32x4 xi0 = xq[pp & 1][j][0], xi1 = xq[pp & 1][j][1];
;                     f32x4 xo0 = gv[0] * acc[ai][bj][m][0], xo1 = gv[1] * acc[ai][bj][m][1];
;                     if (LAZY) { xo0 = xo0 + xi0 * lg[0] * rl[ai][m]; xo1 = xo1 + xi1 * lg[1] * rl[ai][m]; } else { xo0 = xo0 + xi0; xo1 = xo1 + xi1; }
;                     *(f32x4*)(xout + off) = xo0; *(f32x4*)(xout + off + 4) = xo1;
;                     if (aout) { const f32x4 a0 = xo0 * wv[0], a1 = xo1 * wv[1]; u32x4 w; w.x = cvt_pk_bf16(a0[0], a0[1]); w.y = cvt_pk_bf16(a0[2], a0[3]); w.z = cvt_pk_bf16(a1[0], a1[1]); w.w = cvt_pk_bf16(a1[2], a1[3]);
;                         *(u32x4*)(aout + off) = w;
;                         sq[ai][m] += ((xo0[0] * xo0[0] + xo0[1] * xo0[1]) + (xo0[2] * xo0[2] + xo0[3] * xo0[3])) + ((xo1[0] * xo1[0] + xo1[1] * xo1[1]) + (xo1[2] * xo1[2] + xo1[3] * xo1[3]));
;                         if (WG2) { const f32x4 b0 = xo0 * w2[0], b1 = xo1 * w2[1]; sqb[ai][m] += ((b0[0] * b0[0] + b0[1] * b0[1]) + (b0[2] * b0[2] + b0[3] * b0[3])) + ((b1[0] * b1[0] + b1[1] * b1[1]) + (b1[2] * b1[2] + b1[3] * b1[3])); } } }
.LBB0_513:
	s_waitcnt vmcnt(0)
	v_pk_fma_f32 v[138:139], v[70:71], v[190:191], v[138:139]
	v_pk_fma_f32 v[136:137], v[68:69], v[192:193], v[136:137]
	v_pk_fma_f32 v[130:131], v[66:67], v[188:189], v[130:131]
	v_pk_fma_f32 v[128:129], v[64:65], v[174:175], v[128:129]
	v_lshl_add_u64 v[144:145], v[194:195], 2, s[28:29]
	s_and_b64 vcc, exec, s[8:9]
	global_store_dwordx4 v[144:145], v[136:139], off
	global_store_dwordx4 v[144:145], v[128:131], off offset:16
	s_cbranch_vccnz .LBB0_515
	v_pk_mul_f32 v[146:147], v[184:185], v[138:139]
	v_pk_mul_f32 v[144:145], v[182:183], v[136:137]
	v_pk_mul_f32 v[148:149], v[186:187], v[130:131]
	v_pk_mul_f32 v[150:151], v[180:181], v[128:129]
	v_cvt_pk_bf16_f32 v144, v144, v145
	v_cvt_pk_bf16_f32 v145, v146, v147
	s_nop 0
	v_cvt_pk_bf16_f32 v146, v150, v151
	v_cvt_pk_bf16_f32 v147, v148, v149
	v_lshl_add_u64 v[148:149], v[194:195], 1, s[26:27]
	global_store_dwordx4 v[148:149], v[144:147], off
	s_nop 1
	v_mov_b32_e32 v145, v128
	v_mov_b32_e32 v128, v137
	v_mov_b32_e32 v137, v130
	v_mov_b32_e32 v130, v139
	v_mov_b32_e32 v144, v136
	v_pk_mul_f32 v[128:129], v[128:129], v[128:129]
	v_mov_b32_e32 v136, v138
	v_pk_mul_f32 v[130:131], v[130:131], v[130:131]
	v_pk_fma_f32 v[128:129], v[144:145], v[144:145], v[128:129]
	v_pk_fma_f32 v[130:131], v[136:137], v[136:137], v[130:131]
	s_nop 0
	v_pk_add_f32 v[128:129], v[128:129], v[130:131]
	s_nop 0
	v_add_f32_e32 v128, v128, v129
	v_add_f32_e32 v203, v203, v128
.LBB0_515:
	s_nop 0
	v_add_u32_e32 v128, 0x8000, v198
	v_mov_b32_e32 v129, v177
	v_lshl_add_u64 v[128:129], v[128:129], 2, s[34:35]
	global_load_dwordx4 v[144:147], v[128:129], off offset:16
	global_load_dwordx4 v[148:151], v[128:129], off
	v_add_u32_e32 v128, 0xc000, v198
	v_mov_b32_e32 v129, v177
	v_lshl_add_u64 v[136:137], v[128:129], 2, s[34:35]
	global_load_dwordx4 v[128:131], v[136:137], off offset:16
	s_nop 0
	global_load_dwordx4 v[136:139], v[136:137], off
	v_add_u32_e32 v194, 0x20000, v176
	v_mov_b32_e32 v195, v177
	s_waitcnt vmcnt(0)
	v_pk_fma_f32 v[158:159], v[54:55], v[190:191], v[158:159]
	v_pk_fma_f32 v[156:157], v[52:53], v[192:193], v[156:157]
	v_pk_fma_f32 v[154:155], v[50:51], v[188:189], v[154:155]
	v_pk_fma_f32 v[152:153], v[48:49], v[174:175], v[152:153]
	v_lshl_add_u64 v[196:197], v[194:195], 2, s[28:29]
	s_and_b64 vcc, exec, s[8:9]
	global_store_dwordx4 v[196:197], v[156:159], off
	global_store_dwordx4 v[196:197], v[152:155], off offset:16
	s_cbranch_vccnz .LBB0_517
	v_pk_mul_f32 v[198:199], v[184:185], v[158:159]
	v_pk_mul_f32 v[196:197], v[182:183], v[156:157]
	v_lshl_add_u64 v[194:195], v[194:195], 1, s[26:27]
	v_pk_mul_f32 v[208:209], v[186:187], v[154:155]
	v_pk_mul_f32 v[210:211], v[180:181], v[152:153]
	v_cvt_pk_bf16_f32 v196, v196, v197
	v_cvt_pk_bf16_f32 v197, v198, v199
	s_nop 0
	v_cvt_pk_bf16_f32 v198, v210, v211
	v_cvt_pk_bf16_f32 v199, v208, v209
	global_store_dwordx4 v[194:195], v[196:199], off
	v_mov_b32_e32 v195, v152
	v_mov_b32_e32 v152, v157
	v_mov_b32_e32 v157, v154
	v_mov_b32_e32 v154, v159
	v_mov_b32_e32 v194, v156
	v_pk_mul_f32 v[152:153], v[152:153], v[152:153]
	v_mov_b32_e32 v156, v158
	v_pk_mul_f32 v[154:155], v[154:155], v[154:155]
	v_pk_fma_f32 v[152:153], v[194:195], v[194:195], v[152:153]
	v_pk_fma_f32 v[154:155], v[156:157], v[156:157], v[154:155]
	s_nop 0
	v_pk_add_f32 v[152:153], v[152:153], v[154:155]
	s_nop 0
	v_add_f32_e32 v152, v152, v153
	v_add_f32_e32 v201, v201, v152
; __device__ __forceinline__ unsigned cvt_pk_bf16(float lo, float hi) { unsigned r; asm volatile("v_cvt_pk_bf16_f32 %0, %1, %2" : "=v"(r) : "v"(lo), "v"(hi)); return r; }
; #define RES_LD(buf, pp) do { _Pragma("unroll") for (int j = 0; j < 2; ++j) { const int i_ = 2 * (pp) + j; const unsigned off_ = (row0 + (i_ >> 2) * HALF + (i_ & 3) * 16) * 1024u + col; \
;                 xq[buf][j][0] = *(const f32x4*)(xin + off_); xq[buf][j][1] = *(const f32x4*)(xin + off_ + 4); } } while (0)
;     static __device__ __forceinline__ void run(const f32x4 (&acc)[2][2][4][2], const Unit& u, int wr, int wc, int fr, int fq, const float* xin, float* xout, const float* gate, float gs, const float* lazy_ssq, const float* lazy_g, ...
;     ...
;             constexpr bool DEEP = !LAZY && !WG2;
;             if (DEEP) RES_LD(0, 0);
; #pragma unroll
;             for (int pp = 0; pp < 4; ++pp) {
;                 if (DEEP) { if (pp < 3) RES_LD((pp + 1) & 1, pp + 1); } else RES_LD(pp & 1, pp);
; #pragma unroll
;                 for (int j = 0; j < 2; ++j) { const int i_ = 2 * pp + j, ai = i_ >> 2, m = i_ & 3; const unsigned off = (row0 + ai * HALF + m * 16) * 1024u + col;
;                     const f32x4 xi0 = xq[pp & 1][j][0], xi1 = xq[pp & 1][j][1];
;                     f32x4 xo0 = gv[0] * acc[ai][bj][m][0], xo1 = gv[1] * acc[ai][bj][m][1];
;                     if (LAZY) { xo0 = xo0 + xi0 * lg[0] * rl[ai][m]; xo1 = xo1 + xi1 * lg[1] * rl[ai][m]; } else { xo0 = xo0 + xi0; xo1 = xo1 + xi1; }
;                     *(f32x4*)(xout + off) = xo0; *(f32x4*)(xout + off + 4) = xo1;
;                     if (aout) { const f32x4 a0 = xo0 * wv[0], a1 = xo1 * wv[1]; u32x4 w; w.x = cvt_pk_bf16(a0[0], a0[1]); w.y = cvt_pk_bf16(a0[2], a0[3]); w.z = cvt_pk_bf16(a1[0], a1[1]); w.w = cvt_pk_bf16(a1[2], a1[3]);
;                         *(u32x4*)(aout + off) = w;
;                         sq[ai][m] += ((xo0[0] * xo0[0] + xo0[1] * xo0[1]) + (xo0[2] * xo0[2] + xo0[3] * xo0[3])) + ((xo1[0] * xo1[0] + xo1[1] * xo1[1]) + (xo1[2] * xo1[2] + xo1[3] * xo1[3]));
;                         if (WG2) { const f32x4 b0 = xo0 * w2[0], b1 = xo1 * w2[1]; sqb[ai][m] += ((b0[0] * b0[0] + b0[1] * b0[1]) + (b0[2] * b0[2] + b0[3] * b0[3])) + ((b1[0] * b1[0] + b1[1] * b1[1]) + (b1[2] * b1[2] + b1[3] * b1[3])); } } }
.LBB0_517:
	s_nop 0
	v_add_u32_e32 v152, 0x24000, v176
	v_mov_b32_e32 v153, v177
	s_waitcnt vmcnt(0)
	v_pk_fma_f32 v[142:143], v[38:39], v[190:191], v[142:143]
	v_pk_fma_f32 v[140:141], v[36:37], v[192:193], v[140:141]
	v_pk_fma_f32 v[134:135], v[34:35], v[188:189], v[134:135]
	v_pk_fma_f32 v[132:133], v[32:33], v[174:175], v[132:133]
	v_lshl_add_u64 v[154:155], v[152:153], 2, s[28:29]
	s_and_b64 vcc, exec, s[8:9]
	global_store_dwordx4 v[154:155], v[140:143], off
	global_store_dwordx4 v[154:155], v[132:135], off offset:16
	s_cbranch_vccnz .LBB0_519
	v_pk_mul_f32 v[156:157], v[184:185], v[142:143]
	v_pk_mul_f32 v[154:155], v[182:183], v[140:141]
	v_lshl_add_u64 v[152:153], v[152:153], 1, s[26:27]
	v_pk_mul_f32 v[158:159], v[186:187], v[134:135]
	v_pk_mul_f32 v[194:195], v[180:181], v[132:133]
	v_cvt_pk_bf16_f32 v154, v154, v155
	v_cvt_pk_bf16_f32 v155, v156, v157
	s_nop 0
	v_cvt_pk_bf16_f32 v156, v194, v195
	v_cvt_pk_bf16_f32 v157, v158, v159
	global_store_dwordx4 v[152:153], v[154:157], off
	v_mov_b32_e32 v153, v132
	v_mov_b32_e32 v132, v141
	v_mov_b32_e32 v141, v134
	v_mov_b32_e32 v134, v143
	v_mov_b32_e32 v152, v140
	v_pk_mul_f32 v[132:133], v[132:133], v[132:133]
	v_mov_b32_e32 v140, v142
	v_pk_mul_f32 v[134:135], v[134:135], v[134:135]
	v_pk_fma_f32 v[132:133], v[152:153], v[152:153], v[132:133]
	v_pk_fma_f32 v[134:135], v[140:141], v[140:141], v[134:135]
	s_nop 0
	v_pk_add_f32 v[132:133], v[132:133], v[134:135]
	s_nop 0
	v_add_f32_e32 v132, v132, v133
	v_add_f32_e32 v200, v200, v132
.LBB0_519:
	v_add_u32_e32 v152, 0x28000, v176
	v_mov_b32_e32 v153, v177
	s_waitcnt vmcnt(0)
	v_pk_fma_f32 v[134:135], v[22:23], v[190:191], v[150:151]
	v_pk_fma_f32 v[132:133], v[20:21], v[192:193], v[148:149]
	v_pk_fma_f32 v[142:143], v[18:19], v[188:189], v[146:147]
	v_pk_fma_f32 v[140:141], v[16:17], v[174:175], v[144:145]
	v_lshl_add_u64 v[144:145], v[152:153], 2, s[28:29]
	s_and_b64 vcc, exec, s[8:9]
	global_store_dwordx4 v[144:145], v[132:135], off
	global_store_dwordx4 v[144:145], v[140:143], off offset:16
	s_cbranch_vccnz .LBB0_521
	v_pk_mul_f32 v[146:147], v[184:185], v[134:135]
	v_pk_mul_f32 v[144:145], v[182:183], v[132:133]
	v_pk_mul_f32 v[148:149], v[186:187], v[142:143]
	v_pk_mul_f32 v[150:151], v[180:181], v[140:141]
	v_cvt_pk_bf16_f32 v144, v144, v145
	v_cvt_pk_bf16_f32 v145, v146, v147
	s_nop 0
	v_cvt_pk_bf16_f32 v146, v150, v151
	v_cvt_pk_bf16_f32 v147, v148, v149
	v_lshl_add_u64 v[148:149], v[152:153], 1, s[26:27]
	global_store_dwordx4 v[148:149], v[144:147], off
	s_nop 1
	v_mov_b32_e32 v145, v140
	v_mov_b32_e32 v140, v133
	v_mov_b32_e32 v144, v132
	v_pk_mul_f32 v[132:133], v[140:141], v[140:141]
	v_mov_b32_e32 v141, v142
	v_mov_b32_e32 v142, v135
	v_mov_b32_e32 v140, v134
	v_pk_mul_f32 v[134:135], v[142:143], v[142:143]
	v_pk_fma_f32 v[132:133], v[144:145], v[144:145], v[132:133]
	v_pk_fma_f32 v[134:135], v[140:141], v[140:141], v[134:135]
	s_nop 0
	v_pk_add_f32 v[132:133], v[132:133], v[134:135]
	s_nop 0
	v_add_f32_e32 v132, v132, v133
	v_add_f32_e32 v206, v206, v132
.LBB0_521:
	v_add_u32_e32 v176, 0x2c000, v176
	s_waitcnt vmcnt(0)
	v_pk_fma_f32 v[134:135], v[6:7], v[190:191], v[138:139]
	v_pk_fma_f32 v[132:133], v[4:5], v[192:193], v[136:137]
	v_pk_fma_f32 v[130:131], v[2:3], v[188:189], v[130:131]
	v_pk_fma_f32 v[128:129], v[0:1], v[174:175], v[128:129]
	v_lshl_add_u64 v[136:137], v[176:177], 2, s[28:29]
	s_and_b64 vcc, exec, s[8:9]
	global_store_dwordx4 v[136:137], v[132:135], off
	global_store_dwordx4 v[136:137], v[128:131], off offset:16
	s_cbranch_vccnz .LBB0_523
	v_pk_mul_f32 v[138:139], v[184:185], v[134:135]
	v_pk_mul_f32 v[136:137], v[182:183], v[132:133]
	v_pk_mul_f32 v[140:141], v[186:187], v[130:131]
	v_pk_mul_f32 v[142:143], v[180:181], v[128:129]
	v_cvt_pk_bf16_f32 v136, v136, v137
	v_cvt_pk_bf16_f32 v137, v138, v139
	s_nop 0
	v_cvt_pk_bf16_f32 v138, v142, v143
	v_cvt_pk_bf16_f32 v139, v140, v141
	v_lshl_add_u64 v[140:141], v[176:177], 1, s[26:27]
	global_store_dwordx4 v[140:141], v[136:139], off
	s_nop 1
	v_mov_b32_e32 v137, v128
	v_mov_b32_e32 v128, v133
	v_mov_b32_e32 v133, v130
	v_mov_b32_e32 v130, v135
	v_mov_b32_e32 v136, v132
	v_pk_mul_f32 v[128:129], v[128:129], v[128:129]
	v_mov_b32_e32 v132, v134
	v_pk_mul_f32 v[130:131], v[130:131], v[130:131]
	v_pk_fma_f32 v[128:129], v[136:137], v[136:137], v[128:129]
	v_pk_fma_f32 v[130:131], v[132:133], v[132:133], v[130:131]
	s_nop 0
	v_pk_add_f32 v[128:129], v[128:129], v[130:131]
	s_nop 0
	v_add_f32_e32 v128, v128, v129
	v_add_f32_e32 v202, v202, v128
